# RWKV chunk records streamed once by the recurrence (LDS-DMA) and the short-conv operand rows also use the non-temporal hint
# speedup vs baseline: 1.0141x; 1.0041x over previous
.LBB0_411:
	v_ashrrev_i32_e32 v3, 31, v2
	v_lshl_add_u64 v[6:7], s[16:17], 0, v[2:3]
	global_load_dwordx4 v[6:9], v[6:7], off nt
	v_add_u32_e32 v5, 0x200, v5
	s_movk_i32 s11, 0x18ff
	v_cmp_lt_i32_e32 vcc, s11, v5
	v_add_u32_e32 v3, 0, v2
	s_or_b64 s[18:19], vcc, s[18:19]
	v_add_u32_e32 v2, 0x2000, v2
	s_waitcnt vmcnt(0)
	ds_write_b128 v3, v[6:9]
	s_andn2_b64 exec, exec, s[18:19]
	s_cbranch_execnz .LBB0_411

.LBB0_414:
	v_ashrrev_i32_e32 v1, 31, v0
	v_lshl_add_u64 v[2:3], s[12:13], 0, v[0:1]
	global_load_dwordx4 v[6:9], v[2:3], off nt
	v_add_u32_e32 v4, 0x200, v4
	s_movk_i32 s15, 0xff
	v_add_u32_e32 v1, 0, v0
	v_cmp_lt_i32_e32 vcc, s15, v4
	v_add_u32_e32 v1, 0x22400, v1
	s_or_b64 s[16:17], vcc, s[16:17]
	v_add_u32_e32 v0, 0x2000, v0
	s_waitcnt vmcnt(0)
	ds_write_b128 v1, v[6:9]
	s_andn2_b64 exec, exec, s[16:17]
	s_cbranch_execnz .LBB0_414

.LBB0_419:
	s_cmpk_gt_u32 s1, 0x7c
	s_cbranch_scc1 .LBB0_422
	s_add_i32 s2, s0, s1
	s_add_i32 s2, s2, 3
	s_ashr_i32 s3, s2, 31
	s_lshl_b64 s[2:3], s[2:3], 12
	v_lshl_add_u64 v[4:5], v[0:1], 0, s[2:3]
	s_add_i32 s2, s1, 3
	s_and_b32 s3, s2, 0xff
	s_mulk_i32 s3, 0xcd
	s_bfe_u32 s3, s3, 0x6000a
	s_mul_i32 s3, s3, 5
	s_sub_i32 s2, s2, s3
	s_and_b32 s2, s2, 0xff
	s_lshl_b32 s2, s2, 12
	s_add_i32 s2, s4, s2
	s_mov_b32 m0, s2
	s_nop 0
	global_load_lds_dwordx4 v[4:5], off nt
	v_lshl_add_u64 v[4:5], v[4:5], 0, s[22:23]
	s_add_i32 m0, s2, 0x400
	s_nop 0
	global_load_lds_dwordx4 v[4:5], off nt
	s_cmpk_gt_u32 s1, 0x79
	s_mov_b64 s[2:3], -1
	s_cbranch_scc1 .LBB0_423

.LBB0_424:
	s_add_i32 s2, s0, s1
	s_add_i32 s2, s2, 6
	v_mad_i64_i32 v[4:5], s[2:3], s2, v209, v[2:3]
	s_add_i32 s2, s1, 6
	s_and_b32 s3, s2, 0xff
	s_mul_i32 s3, s3, 37
	s_lshr_b32 s19, s3, 8
	s_sub_i32 s19, s2, s19
	s_bfe_u32 s19, s19, 0x70001
	s_bfe_u32 s3, s3, 0x80008
	s_add_i32 s19, s19, s3
	s_bfe_u32 s3, s19, 0x60002
	s_mul_i32 s3, s3, 7
	s_sub_i32 s2, s2, s3
	s_and_b32 s2, s2, 0xff
	s_mulk_i32 s2, 0x4800
	s_add_i32 s19, s5, s2
	s_mov_b32 m0, s19
	v_lshl_add_u64 v[6:7], v[4:5], 0, s[22:23]
	global_load_lds_dwordx4 v[4:5], off nt
	s_add_i32 m0, s19, 0x400
	s_mov_b64 s[2:3], 0x800
	global_load_lds_dwordx4 v[6:7], off nt
	v_lshl_add_u64 v[6:7], v[4:5], 0, s[2:3]
	s_add_i32 m0, s19, 0x800
	s_mov_b64 s[2:3], 0xc00
	global_load_lds_dwordx4 v[6:7], off nt
	v_lshl_add_u64 v[6:7], v[4:5], 0, s[2:3]
	s_add_i32 m0, s19, 0xc00
	s_mov_b64 s[2:3], 0x1400
	global_load_lds_dwordx4 v[6:7], off nt
	v_lshl_add_u64 v[6:7], v[4:5], 0, s[46:47]
	s_add_i32 m0, s19, 0x1000
	s_nop 0
	global_load_lds_dwordx4 v[6:7], off nt
	v_lshl_add_u64 v[6:7], v[4:5], 0, s[2:3]
	s_add_i32 m0, s19, 0x1400
	s_mov_b64 s[2:3], 0x1c00
	global_load_lds_dwordx4 v[6:7], off nt
	v_lshl_add_u64 v[6:7], v[4:5], 0, s[66:67]
	s_add_i32 m0, s19, 0x1800
	s_nop 0
	global_load_lds_dwordx4 v[6:7], off nt
	v_lshl_add_u64 v[6:7], v[4:5], 0, s[2:3]
	s_add_i32 m0, s19, 0x1c00
	s_mov_b64 s[2:3], 0x2000
	global_load_lds_dwordx4 v[6:7], off nt
	v_lshl_add_u64 v[4:5], v[4:5], 0, s[2:3]
	s_add_i32 m0, s19, 0x2000
	s_nop 0
	global_load_lds_dwordx4 v[4:5], off nt
	s_waitcnt vmcnt(42)
	s_branch .LBB0_418

.LBB0_926:
	v_ashrrev_i32_e32 v115, 4, v112
	v_and_b32_e32 v106, -4, v115
	v_cmp_gt_i32_e32 vcc, s88, v106
	v_mov_b64_e32 v[0:1], s[16:17]
	v_and_b32_e32 v16, 0x1f8, v113
	v_cndmask_b32_e32 v114, 4, v204, vcc
	v_and_b32_e32 v116, v114, v115
	v_mad_i64_i32 v[0:1], s[2:3], v106, s83, v[0:1]
	v_lshlrev_b32_e32 v156, 1, v16
	v_cmp_eq_u32_e64 s[2:3], 0, v116
	v_lshl_add_u64 v[0:1], v[0:1], 0, v[156:157]
	v_mov_b32_e32 v3, v157
	v_cndmask_b32_e64 v2, 0, v213, s[2:3]
	v_lshl_add_u64 v[2:3], v[0:1], 0, v[2:3]
	v_add_co_u32_e64 v2, s[4:5], s27, v2
	v_cndmask_b32_e64 v4, v214, v213, s[2:3]
	v_mov_b32_e32 v5, v157
	v_addc_co_u32_e64 v3, s[4:5], -1, v3, s[4:5]
	v_lshl_add_u64 v[4:5], v[0:1], 0, v[4:5]
	v_add_co_u32_e64 v4, s[4:5], s27, v4
	v_lshlrev_b32_e32 v104, 2, v16
	s_nop 0
	v_addc_co_u32_e64 v5, s[4:5], -1, v5, s[4:5]
	global_load_dwordx4 v[92:95], v[2:3], off offset:-1024 nt
	global_load_dwordx4 v[72:75], v[4:5], off offset:-3072 nt
	global_load_dwordx4 v[100:103], v[2:3], off offset:-3072 nt
	global_load_dwordx4 v[60:63], v[0:1], off offset:2048 nt
	v_add_co_u32_e64 v2, s[4:5], s72, v0
	v_add_u32_e32 v80, 0xffffc000, v115
	s_nop 0
	v_addc_co_u32_e64 v3, s[4:5], 0, v1, s[4:5]
	global_load_dwordx4 v[76:79], v[4:5], off offset:-1024 nt
	global_load_dwordx4 v[56:59], v[2:3], off offset:3584 nt
	v_add_co_u32_e64 v2, s[4:5], s93, v0
	v_lshrrev_b32_e32 v117, 3, v80
	s_nop 0
	v_addc_co_u32_e64 v3, s[4:5], 0, v1, s[4:5]
	s_movk_i32 s4, 0x3000
	s_nop 0
	v_add_co_u32_e64 v4, s[4:5], s4, v0
	v_mov_b32_e32 v88, 0
	s_nop 0
	v_addc_co_u32_e64 v5, s[4:5], 0, v1, s[4:5]
	v_add_co_u32_e64 v6, s[4:5], s88, v0
	v_mov_b32_e32 v89, 0
	s_nop 0
	v_addc_co_u32_e64 v7, s[4:5], 0, v1, s[4:5]
	s_movk_i32 s4, 0x5000
	s_nop 0
	v_add_co_u32_e64 v8, s[4:5], s4, v0
	v_mov_b32_e32 v90, 0
	s_nop 0
	v_addc_co_u32_e64 v9, s[4:5], 0, v1, s[4:5]
	v_add_co_u32_e64 v10, s[4:5], s45, v0
	global_load_dwordx4 v[40:43], v[6:7], off offset:1024 nt
	global_load_dwordx4 v[48:51], v[8:9], off offset:2560 nt
	v_addc_co_u32_e64 v11, s[4:5], 0, v1, s[4:5]
	global_load_dwordx4 v[68:71], v[0:1], off nt
	global_load_dwordx4 v[36:39], v[0:1], off offset:1024 nt
	global_load_dwordx4 v[64:67], v[2:3], off offset:1536 nt
	global_load_dwordx4 v[32:35], v[2:3], off offset:512 nt
	global_load_dwordx4 v[44:47], v[4:5], off offset:3072 nt
	global_load_dwordx4 v[28:31], v[6:7], off nt
	global_load_dwordx4 v[52:55], v[10:11], off offset:512 nt
	global_load_dwordx4 v[12:15], v[8:9], off offset:3584 nt
	s_nop 0
	global_load_dwordx4 v[0:3], v104, s[12:13] offset:16 nt
	global_load_dwordx4 v[16:19], v104, s[12:13] nt
	global_load_dwordx4 v[8:11], v104, s[12:13] offset:2064 nt
	global_load_dwordx4 v[24:27], v104, s[12:13] offset:2048 nt
	global_load_dwordx4 v[4:7], v104, s[20:21] offset:16 nt
	global_load_dwordx4 v[20:23], v104, s[20:21] nt
	v_cmp_lt_i32_e64 s[4:5], s90, v106
	s_and_b64 s[34:35], s[4:5], s[2:3]
	v_mov_b32_e32 v91, 0
	v_mov_b32_e32 v96, 0
	v_mov_b32_e32 v97, 0
	v_mov_b32_e32 v98, 0
	v_mov_b32_e32 v99, 0
	v_mov_b32_e32 v80, 0
	v_mov_b32_e32 v81, 0
	v_mov_b32_e32 v82, 0
	v_mov_b32_e32 v83, 0
	v_mov_b32_e32 v84, 0
	v_mov_b32_e32 v85, 0
	v_mov_b32_e32 v86, 0
	v_mov_b32_e32 v87, 0
	s_and_saveexec_b64 s[4:5], s[34:35]
	s_cbranch_execz .LBB0_928
	v_lshlrev_b32_e32 v80, 10, v117
	v_ashrrev_i32_e32 v81, 31, v80
	v_lshl_add_u64 v[80:81], v[80:81], 2, s[14:15]
	v_mov_b32_e32 v105, v157
	v_lshl_add_u64 v[96:97], v[80:81], 0, v[104:105]
	global_load_dwordx4 v[80:83], v[96:97], off nt
	global_load_dwordx4 v[84:87], v[96:97], off offset:16 nt
	global_load_dwordx4 v[88:91], v[96:97], off offset:2048 nt
	s_nop 0
	global_load_dwordx4 v[96:99], v[96:97], off offset:2064 nt
